# attention softmax: x-m subtractions issued as packed f32 pairs (bit-identical); first log-forget load of an item not waited alone
# speedup vs baseline: 1.0031x; 1.0005x over previous
; __device__ __forceinline__ void build_ctab(char* lds, const float* LFbh, const int tid) {
;     ...
;     constexpr int PER = 9; const int e0 = tid * PER;
;     float v[PER]; float s = 0.f;
; #pragma unroll
;     for (int i = 0; i < PER; ++i) { const int kk = e0 + i; float x = 0.f; if (kk >= 48 && kk < KVROWS) x = LFbh[kk]; s += x; v[i] = s; }
.LBB0_486:
	s_ashr_i32 s11, s60, 7
	s_bfe_u32 s10, s60, 0x40003
	s_lshl_b32 s8, s11, 4
	v_mov_b32_e32 v155, v186
	s_or_b32 s9, s8, s10
	s_mul_i32 s0, s9, 0x4100
	v_readlane_b32 s2, v248, 52
	v_lshl_add_u32 v128, v155, 3, v155
	s_mul_hi_i32 s1, s9, 0x4100
	v_readlane_b32 s3, v248, 53
	s_add_u32 s0, s2, s0
	v_subrev_u32_e32 v0, 48, v128
	s_addc_u32 s1, s3, s1
	v_cmp_gt_u32_e32 vcc, s6, v0
	v_mov_b32_e32 v0, 0
	s_and_saveexec_b64 s[2:3], vcc
	s_cbranch_execz .LBB0_488
	v_lshl_add_u64 v[0:1], v[128:129], 2, s[0:1]
	global_load_dword v0, v[0:1], off
.LBB0_488:
	s_or_b64 exec, exec, s[2:3]
	v_subrev_u32_e32 v1, 47, v128
	v_cmp_gt_u32_e32 vcc, s6, v1
	v_mov_b32_e32 v3, 0
	v_mov_b32_e32 v1, 0
	s_and_saveexec_b64 s[2:3], vcc
	s_cbranch_execz .LBB0_490
	v_lshl_add_u64 v[4:5], v[128:129], 2, s[0:1]
	global_load_dword v1, v[4:5], off offset:4

; __device__ __forceinline__ void build_ctab(char* lds, const float* LFbh, const int tid) {
;     ...
;     for (int i = 0; i < PER; ++i) { const int kk = e0 + i; float x = 0.f; if (kk >= 48 && kk < KVROWS) x = LFbh[kk]; s += x; v[i] = s; }
;     float incl = s;
; #pragma unroll
;     for (int off = 1; off < 64; off <<= 1) { const float t = __shfl_up(incl, off); if (lane >= off) incl += t; }
;     if (lane == 63) red[wid] = incl;
;     __syncthreads();
;     float base = incl - s;
;     for (int w = 0; w < wid; ++w) base += red[w];
.LBB0_504:
	s_or_b64 exec, exec, s[2:3]
	s_waitcnt vmcnt(0)
	v_add_f32_e32 v0, 0, v0
	v_add_f32_e32 v1, v0, v1
	v_add_f32_e32 v14, v1, v3
	v_add_f32_e32 v15, v14, v10
	v_add_f32_e32 v12, v15, v5
	v_add_f32_e32 v13, v12, v11
	v_add_f32_e32 v10, v13, v7
	v_cmp_lt_i32_e32 vcc, v182, v181
	v_add_f32_e32 v11, v10, v16
	v_add_f32_e32 v3, v11, v9
	v_cndmask_b32_e32 v5, v182, v180, vcc
	v_lshlrev_b32_e32 v5, 2, v5
	ds_bpermute_b32 v5, v5, v3
	v_and_b32_e32 v198, 63, v155
	v_cmp_eq_u32_e32 vcc, 0, v198
	s_waitcnt lgkmcnt(0)
	v_add_f32_e32 v5, v3, v5
	v_cndmask_b32_e32 v5, v5, v3, vcc
	v_cmp_lt_i32_e32 vcc, v183, v181
	s_nop 1
	v_cndmask_b32_e32 v7, v183, v180, vcc
	v_lshlrev_b32_e32 v7, 2, v7
	ds_bpermute_b32 v7, v7, v5
	v_cmp_gt_u32_e32 vcc, 2, v198
	s_waitcnt lgkmcnt(0)
	v_add_f32_e32 v7, v5, v7
	v_cndmask_b32_e32 v5, v7, v5, vcc
	v_cmp_lt_i32_e32 vcc, v184, v181
	s_nop 1
	v_cndmask_b32_e32 v7, v184, v180, vcc
	v_lshlrev_b32_e32 v7, 2, v7
	ds_bpermute_b32 v7, v7, v5
	v_cmp_gt_u32_e32 vcc, 4, v198
	s_waitcnt lgkmcnt(0)
	v_add_f32_e32 v7, v5, v7
	v_cndmask_b32_e32 v5, v7, v5, vcc
	v_cmp_lt_i32_e32 vcc, v185, v181
	s_nop 1
	v_cndmask_b32_e32 v7, v185, v180, vcc
	v_lshlrev_b32_e32 v7, 2, v7
	ds_bpermute_b32 v7, v7, v5
	v_cmp_gt_u32_e32 vcc, 8, v198
	s_waitcnt lgkmcnt(0)
	v_add_f32_e32 v7, v5, v7
	v_cndmask_b32_e32 v5, v7, v5, vcc
	v_cmp_lt_i32_e32 vcc, v187, v181
	s_nop 1
	v_cndmask_b32_e32 v7, v187, v180, vcc
	v_lshlrev_b32_e32 v7, 2, v7
	ds_bpermute_b32 v7, v7, v5
	v_cmp_gt_u32_e32 vcc, 16, v198
	s_waitcnt lgkmcnt(0)
	v_add_f32_e32 v7, v5, v7
	v_cndmask_b32_e32 v5, v7, v5, vcc
	v_cmp_lt_i32_e32 vcc, v188, v181
	s_nop 1
	v_cndmask_b32_e32 v7, v188, v180, vcc
	v_lshlrev_b32_e32 v7, 2, v7
	ds_bpermute_b32 v7, v7, v5
	v_cmp_eq_u32_e32 vcc, 63, v198
	s_waitcnt lgkmcnt(0)
	v_add_f32_e32 v9, v5, v7
	v_ashrrev_i32_e32 v7, 6, v155
	s_and_saveexec_b64 s[0:1], vcc
	v_lshl_add_u32 v16, v7, 2, 0
	v_add_u32_e32 v16, 0x1c900, v16
	ds_write_b32 v16, v9
	s_or_b64 exec, exec, s[0:1]
	v_cmp_gt_u32_e64 s[0:1], 32, v198
	v_cmp_lt_i32_e32 vcc, 0, v7
	s_waitcnt lgkmcnt(0)
	v_cndmask_b32_e64 v5, v9, v5, s[0:1]
	v_sub_f32_e32 v16, v5, v3
	s_barrier
	s_and_saveexec_b64 s[2:3], vcc
	s_cbranch_execz .LBB0_516
	v_cmp_lt_u32_e32 vcc, 7, v7
	v_mov_b32_e32 v5, 0
	s_and_saveexec_b64 s[4:5], vcc
	s_cbranch_execz .LBB0_511
	v_and_b32_e32 v5, 0x7ffffff8, v7
	s_mov_b32 s12, 0
	s_mov_b64 s[6:7], 0
	v_readlane_b32 s13, v247, 1

; #define LAS __attribute__((address_space(3)))
; __device__ __forceinline__ void partialSM(f32x16& p0, f32x16& p1, float& m_reg, float& mn, float& alpha) {
;     ...
;     for (int r = 0; r < 16; ++r) p0[r] = p0[r] - mn;
; #pragma unroll
;     for (int r = 0; r < 16; ++r) p1[r] = p1[r] - mn;
; #pragma unroll
;     for (int r = 0; r < 16; ++r) p0[r] = __builtin_amdgcn_exp2f(p0[r]);
; }
; __device__ __forceinline__ void finishSM(f32x16& p0, f32x16& p1, float alpha, float& l_reg, bf16x8& pa0, bf16x8& pa1, bf16x8& pa2, bf16x8& pa3) {
; #pragma unroll
;     for (int r = 0; r < 16; ++r) p1[r] = __builtin_amdgcn_exp2f(p1[r]);
;     float ps = 0;
; #pragma unroll
;     for (int r = 0; r < 16; ++r) ps += p0[r];
; #pragma unroll
;     for (int r = 0; r < 16; ++r) ps += p1[r];
;     { auto rr = __builtin_amdgcn_permlane32_swap(__float_as_uint(ps), __float_as_uint(ps), false, false);
;       ps = __uint_as_float(rr[0]) + __uint_as_float(rr[1]); }
;     l_reg = l_reg * alpha + ps;
;     ...
;     PK4(p0, 0, pa0); PK4(p0, 8, pa1); PK4(p1, 0, pa2); PK4(p1, 8, pa3);
;     ...
; }
; __device__ __forceinline__ void qkt(f32x16& p0, f32x16& p1, const char* Kslot, int r32, int hi, const bf16x8* qr, const LAS f32x4* cp) {
; #pragma unroll
;     for (int g = 0; g < 4; ++g) { const f32x4 c0 = cp[2 * g], c1 = cp[8 + 2 * g];
; #pragma unroll
;         for (int j = 0; j < 4; ++j) { p0[4 * g + j] = c0[j]; p1[4 * g + j] = c1[j]; } }
;     const char* kb[4];
; #pragma unroll
;     for (int dd = 0; dd < 4; ++dd) kb[dd] = Kslot + KSWZ(r32, (dd * 16 + hi * 8) * 2);
; #pragma unroll
;     for (int d0 = 0; d0 < 8; ++d0) { const char* a = kb[d0 & 3] + (d0 >> 2) * 128;
;         bf16x8 b0 = *reinterpret_cast<const bf16x8*>(a);
;         bf16x8 b1 = *reinterpret_cast<const bf16x8*>(a + 32 * 256);
;         p0 = __builtin_amdgcn_mfma_f32_32x32x16_bf16(b0, qr[d0], p0, 0, 0, 0);
;         p1 = __builtin_amdgcn_mfma_f32_32x32x16_bf16(b1, qr[d0], p1, 0, 0, 0); }
.LBB0_537:
	v_cndmask_b32_e64 v154, v164, v154, s[2:3]
	v_pk_add_f32 v[80:81], v[80:81], v[154:155] op_sel_hi:[1,0] neg_lo:[0,1] neg_hi:[0,1]
	v_pk_add_f32 v[82:83], v[82:83], v[154:155] op_sel_hi:[1,0] neg_lo:[0,1] neg_hi:[0,1]
	v_pk_add_f32 v[84:85], v[84:85], v[154:155] op_sel_hi:[1,0] neg_lo:[0,1] neg_hi:[0,1]
	v_pk_add_f32 v[86:87], v[86:87], v[154:155] op_sel_hi:[1,0] neg_lo:[0,1] neg_hi:[0,1]
	v_pk_add_f32 v[88:89], v[88:89], v[154:155] op_sel_hi:[1,0] neg_lo:[0,1] neg_hi:[0,1]
	v_pk_add_f32 v[90:91], v[90:91], v[154:155] op_sel_hi:[1,0] neg_lo:[0,1] neg_hi:[0,1]
	v_pk_add_f32 v[92:93], v[92:93], v[154:155] op_sel_hi:[1,0] neg_lo:[0,1] neg_hi:[0,1]
	v_pk_add_f32 v[94:95], v[94:95], v[154:155] op_sel_hi:[1,0] neg_lo:[0,1] neg_hi:[0,1]
	v_pk_add_f32 v[164:165], v[64:65], v[154:155] op_sel_hi:[1,0] neg_lo:[0,1] neg_hi:[0,1]
	v_pk_add_f32 v[166:167], v[66:67], v[154:155] op_sel_hi:[1,0] neg_lo:[0,1] neg_hi:[0,1]
	v_pk_add_f32 v[168:169], v[68:69], v[154:155] op_sel_hi:[1,0] neg_lo:[0,1] neg_hi:[0,1]
	v_pk_add_f32 v[170:171], v[70:71], v[154:155] op_sel_hi:[1,0] neg_lo:[0,1] neg_hi:[0,1]
	v_pk_add_f32 v[172:173], v[72:73], v[154:155] op_sel_hi:[1,0] neg_lo:[0,1] neg_hi:[0,1]
	v_pk_add_f32 v[174:175], v[74:75], v[154:155] op_sel_hi:[1,0] neg_lo:[0,1] neg_hi:[0,1]
	v_sub_f32_e32 v176, v76, v154
	v_exp_f32_e32 v177, v80
	v_exp_f32_e32 v178, v81
	v_exp_f32_e32 v179, v82
	v_exp_f32_e32 v221, v83
	v_exp_f32_e32 v222, v84
	v_exp_f32_e32 v223, v85
	v_exp_f32_e32 v224, v86
	v_exp_f32_e32 v225, v87
	v_exp_f32_e32 v226, v88
	v_exp_f32_e32 v227, v89
	v_exp_f32_e32 v228, v90
	v_exp_f32_e32 v229, v91
	v_exp_f32_e32 v230, v92
	v_exp_f32_e32 v231, v93
	v_exp_f32_e32 v232, v94
	v_exp_f32_e32 v233, v95
	v_sub_f32_e32 v234, v77, v154
	v_sub_f32_e32 v235, v78, v154
	v_sub_f32_e32 v236, v79, v154
	s_add_i32 s2, s76, 0
	v_add_u32_e32 v237, s2, v193
	ds_read_b128 v[80:83], v217 offset:256
	ds_read_b128 v[84:87], v217 offset:288
	ds_read_b128 v[64:67], v217 offset:384
	ds_read_b128 v[68:71], v217 offset:416
	ds_read_b128 v[88:91], v217 offset:320
	ds_read_b128 v[72:75], v217 offset:448
	ds_read_b128 v[92:95], v217 offset:352
	ds_read_b128 v[76:79], v217 offset:480
	ds_read_b128 v[156:159], v237 offset:49152
	ds_read_b128 v[160:163], v237 offset:57344
	v_add_u32_e32 v238, s2, v194
	v_add_u32_e32 v239, s2, v195
	s_waitcnt lgkmcnt(0)
	v_mfma_f32_32x32x16_bf16 v[80:95], v[156:159], v[96:99], v[80:95]
	v_add_u32_e32 v240, s2, v196
	v_exp_f32_e32 v167, v167
	v_exp_f32_e32 v168, v168
	v_exp_f32_e32 v169, v169
	v_exp_f32_e32 v170, v170
	v_exp_f32_e32 v171, v171
	v_exp_f32_e32 v172, v172
	v_mfma_f32_32x32x16_bf16 v[64:79], v[160:163], v[96:99], v[64:79]
	ds_read_b128 v[156:159], v238 offset:49152
	ds_read_b128 v[160:163], v238 offset:57344
	v_exp_f32_e32 v173, v173
	v_exp_f32_e32 v174, v174
	v_exp_f32_e32 v175, v175
	v_exp_f32_e32 v176, v176
	v_exp_f32_e32 v234, v234
	v_exp_f32_e32 v235, v235
	s_waitcnt lgkmcnt(0)
	v_mfma_f32_32x32x16_bf16 v[80:95], v[156:159], v[100:103], v[80:95]
	v_exp_f32_e32 v236, v236
	v_mfma_f32_32x32x16_bf16 v[64:79], v[160:163], v[100:103], v[64:79]
	ds_read_b128 v[156:159], v239 offset:49152
	ds_read_b128 v[160:163], v239 offset:57344
	s_waitcnt lgkmcnt(0)
	v_mfma_f32_32x32x16_bf16 v[80:95], v[156:159], v[104:107], v[80:95]
	v_mfma_f32_32x32x16_bf16 v[64:79], v[160:163], v[104:107], v[64:79]
	ds_read_b128 v[156:159], v240 offset:49152
	ds_read_b128 v[160:163], v240 offset:57344
	s_waitcnt lgkmcnt(0)
	v_mfma_f32_32x32x16_bf16 v[80:95], v[156:159], v[108:111], v[80:95]
	v_mfma_f32_32x32x16_bf16 v[64:79], v[160:163], v[108:111], v[64:79]
	v_xor_b32_e32 v249, 0x80, v237
	v_xor_b32_e32 v250, 0x80, v238
	v_xor_b32_e32 v251, 0x80, v239
	v_xor_b32_e32 v252, 0x80, v240
	ds_read_b128 v[156:159], v249 offset:49152
	ds_read_b128 v[160:163], v249 offset:57344
	v_exp_f32_e32 v237, v164
	s_waitcnt lgkmcnt(0)
	v_mfma_f32_32x32x16_bf16 v[80:95], v[156:159], v[112:115], v[80:95]
	v_mfma_f32_32x32x16_bf16 v[64:79], v[160:163], v[112:115], v[64:79]
	ds_read_b128 v[156:159], v250 offset:49152
	ds_read_b128 v[160:163], v250 offset:57344
	v_exp_f32_e32 v238, v165
	s_waitcnt lgkmcnt(0)
	v_mfma_f32_32x32x16_bf16 v[80:95], v[156:159], v[116:119], v[80:95]
	v_mfma_f32_32x32x16_bf16 v[64:79], v[160:163], v[116:119], v[64:79]
	ds_read_b128 v[156:159], v251 offset:49152
	ds_read_b128 v[160:163], v251 offset:57344
	v_exp_f32_e32 v239, v166
	s_waitcnt lgkmcnt(0)
	v_mfma_f32_32x32x16_bf16 v[80:95], v[156:159], v[120:123], v[80:95]
	v_mfma_f32_32x32x16_bf16 v[64:79], v[160:163], v[120:123], v[64:79]
	ds_read_b128 v[156:159], v252 offset:49152
	ds_read_b128 v[160:163], v252 offset:57344
	s_waitcnt lgkmcnt(0)
	v_mfma_f32_32x32x16_bf16 v[80:95], v[156:159], v[124:127], v[80:95]
	v_add_f32_e32 v156, 0, v177
	v_add_f32_e32 v156, v178, v156
	v_add_f32_e32 v156, v179, v156
	v_add_f32_e32 v156, v221, v156
	v_add_f32_e32 v156, v222, v156
	v_add_f32_e32 v156, v223, v156
	v_add_f32_e32 v156, v224, v156
	v_add_f32_e32 v156, v225, v156
	v_add_f32_e32 v156, v226, v156
	v_add_f32_e32 v156, v227, v156
	v_add_f32_e32 v156, v228, v156
	v_add_f32_e32 v156, v229, v156
	v_add_f32_e32 v156, v230, v156
	v_add_f32_e32 v156, v231, v156
	v_add_f32_e32 v156, v232, v156
	v_add_f32_e32 v156, v233, v156
	v_add_f32_e32 v156, v237, v156
	v_add_f32_e32 v156, v238, v156
	v_add_f32_e32 v156, v239, v156
	v_add_f32_e32 v156, v167, v156
	v_add_f32_e32 v156, v168, v156
	v_add_f32_e32 v156, v169, v156
	v_add_f32_e32 v156, v170, v156
	v_add_f32_e32 v156, v171, v156
	v_add_f32_e32 v156, v172, v156
	v_add_f32_e32 v156, v173, v156
	v_mfma_f32_32x32x16_bf16 v[64:79], v[160:163], v[124:127], v[64:79]
	v_add_f32_e32 v156, v174, v156
	v_add_f32_e32 v156, v175, v156
	v_add_f32_e32 v156, v176, v156
	v_add_f32_e32 v156, v234, v156
	v_add_f32_e32 v156, v235, v156
	v_add_f32_e32 v156, v236, v156
	v_mov_b32_e32 v157, v156
	s_nop 1
	v_permlane32_swap_b32_e32 v156, v157
	v_cvt_pk_bf16_f32 v158, v177, v178
	v_cvt_pk_bf16_f32 v159, v179, v221
	v_cvt_pk_bf16_f32 v160, v222, v223
	v_cvt_pk_bf16_f32 v161, v224, v225
	v_cvt_pk_bf16_f32 v162, v226, v227
	v_cvt_pk_bf16_f32 v163, v228, v229
	v_cvt_pk_bf16_f32 v164, v230, v231
	v_cvt_pk_bf16_f32 v165, v232, v233
	v_cvt_pk_bf16_f32 v166, v237, v238
	v_cvt_pk_bf16_f32 v167, v239, v167
	v_cvt_pk_bf16_f32 v168, v168, v169
	v_cvt_pk_bf16_f32 v169, v170, v171
	v_cvt_pk_bf16_f32 v170, v172, v173
	v_cvt_pk_bf16_f32 v171, v174, v175
	v_cvt_pk_bf16_f32 v172, v176, v234
	v_cvt_pk_bf16_f32 v173, v235, v236
	s_nop 0
	v_permlane32_swap_b32_e32 v158, v160
	v_permlane32_swap_b32_e32 v159, v161
	v_permlane32_swap_b32_e32 v162, v164
	v_permlane32_swap_b32_e32 v163, v165
	v_permlane32_swap_b32_e32 v166, v168
	v_permlane32_swap_b32_e32 v167, v169
	v_permlane32_swap_b32_e32 v170, v172
	v_permlane32_swap_b32_e32 v171, v173
	v_add_u32_e32 v178, s73, v192
	s_cmp_le_i32 s92, s91
	s_cbranch_scc0 .Lband_1
; #define SBAR() __builtin_amdgcn_sched_barrier(0)
; #define PV_RD(d0, kh, X) do { constexpr int b_ = v_rd_off(d0, 2 * (kh), 0); TRRD(X##l0, b_); TRRD(X##h0, b_ + 2048); TRRD(X##l1, b_ + 4096); TRRD(X##h1, b_ + 6144); } while (0)
; #define PV_MM(d0, X, PA, PB) do { \
;         o[d0] = __builtin_amdgcn_mfma_f32_32x32x16_bf16(PA, (bf16x8){X##l0[0], X##l0[1], X##l0[2], X##l0[3], X##h0[0], X##h0[1], X##h0[2], X##h0[3]}, o[d0], 0, 0, 0);   \
;         o[d0] = __builtin_amdgcn_mfma_f32_32x32x16_bf16(PB, (bf16x8){X##l1[0], X##l1[1], X##l1[2], X##l1[3], X##h1[0], X##h1[1], X##h1[2], X##h1[3]}, o[d0], 0, 0, 0); } while (0)
; #define PV_W4() do { asm volatile("s_waitcnt lgkmcnt(4)" ::: "memory"); SBAR(); } while (0)
; #define PV_W0() do { asm volatile("s_waitcnt lgkmcnt(0)" ::: "memory"); SBAR(); } while (0)
; __device__ __forceinline__ void partialSM(f32x16& p0, f32x16& p1, float& m_reg, float& mn, float& alpha) {
;     float pmax = p0[0];
; #pragma unroll
;     for (int r = 1; r < 16; ++r) pmax = fmaxf(pmax, p0[r]);
; #pragma unroll
;     for (int r = 0; r < 16; ++r) pmax = fmaxf(pmax, p1[r]);
;     { auto rr = __builtin_amdgcn_permlane32_swap(__float_as_uint(pmax), __float_as_uint(pmax), false, false);
;       pmax = fmaxf(__uint_as_float(rr[0]), __uint_as_float(rr[1])); }
;     if (__builtin_expect(__all((pmax - m_reg) <= THR2), 1)) { mn = m_reg; alpha = 1.f; }
;     else { mn = fmaxf(m_reg, pmax); alpha = __builtin_amdgcn_exp2f(m_reg - mn); m_reg = mn; }
; __device__ __forceinline__ void pv_tile(f32x16* o, int vb0, bf16x8 pa0, bf16x8 pa1, bf16x8 pa2, bf16x8 pa3) {
;     ...
;     s16x4 al0, al1, ah0, ah1, bl0, bl1, bh0, bh1;
;     PV_RD(0, 0, a);
;     PV_RD(0, 1, b); PV_W4(); PV_MM(0, a, pa0, pa1); SBAR();
;     PV_RD(1, 0, a); PV_W4(); PV_MM(0, b, pa2, pa3); SBAR();
;     PV_RD(1, 1, b); PV_W4(); PV_MM(1, a, pa0, pa1); SBAR();
;     PV_RD(2, 0, a); PV_W4(); PV_MM(1, b, pa2, pa3); SBAR();
;     PV_RD(2, 1, b); PV_W4(); PV_MM(2, a, pa0, pa1); SBAR();
;     PV_RD(3, 0, a); PV_W4(); PV_MM(2, b, pa2, pa3); SBAR();
;     PV_RD(3, 1, b); PV_W4(); PV_MM(3, a, pa0, pa1); SBAR();
;     PV_W0(); PV_MM(3, b, pa2, pa3);
	ds_read_b64_tr_b16 v[174:175], v178 offset:0
	ds_read_b64_tr_b16 v[176:177], v178 offset:0x800
	ds_read_b64_tr_b16 v[222:223], v178 offset:0x1000
	ds_read_b64_tr_b16 v[224:225], v178 offset:0x1800
	ds_read_b64_tr_b16 v[226:227], v178 offset:0x2000
	ds_read_b64_tr_b16 v[228:229], v178 offset:0x2800
	ds_read_b64_tr_b16 v[230:231], v178 offset:0x3000
	ds_read_b64_tr_b16 v[232:233], v178 offset:0x3800
	s_waitcnt lgkmcnt(4)
	s_nop 0
	v_mfma_f32_32x32x16_bf16 v[48:63], v[158:161], v[174:177], v[48:63]
	v_max_f32_e32 v253, v81, v81
	v_max_f32_e32 v254, v80, v80
	v_mfma_f32_32x32x16_bf16 v[48:63], v[162:165], v[222:225], v[48:63]
	v_max_f32_e32 v253, v254, v253
	v_max3_f32 v253, v253, v82, v83
	ds_read_b64_tr_b16 v[174:175], v178 offset:0x200
	ds_read_b64_tr_b16 v[176:177], v178 offset:0xa00
	ds_read_b64_tr_b16 v[222:223], v178 offset:0x1200
	ds_read_b64_tr_b16 v[224:225], v178 offset:0x1a00
	s_waitcnt lgkmcnt(4)
	v_mfma_f32_32x32x16_bf16 v[48:63], v[166:169], v[226:229], v[48:63]
	v_max3_f32 v253, v253, v84, v85
	v_max3_f32 v253, v253, v86, v87
	v_mfma_f32_32x32x16_bf16 v[48:63], v[170:173], v[230:233], v[48:63]
	v_max3_f32 v253, v253, v88, v89
	v_max3_f32 v253, v253, v90, v91
	ds_read_b64_tr_b16 v[226:227], v178 offset:0x2200
	ds_read_b64_tr_b16 v[228:229], v178 offset:0x2a00
	ds_read_b64_tr_b16 v[230:231], v178 offset:0x3200
	ds_read_b64_tr_b16 v[232:233], v178 offset:0x3a00
	s_waitcnt lgkmcnt(4)
	v_mfma_f32_32x32x16_bf16 v[32:47], v[158:161], v[174:177], v[32:47]
	v_max3_f32 v253, v253, v92, v93
	v_max3_f32 v253, v253, v94, v95
	v_mfma_f32_32x32x16_bf16 v[32:47], v[162:165], v[222:225], v[32:47]
	v_max3_f32 v253, v253, v64, v65
	v_max3_f32 v253, v253, v66, v67
	ds_read_b64_tr_b16 v[174:175], v178 offset:0x400
	ds_read_b64_tr_b16 v[176:177], v178 offset:0xc00
	ds_read_b64_tr_b16 v[222:223], v178 offset:0x1400
	ds_read_b64_tr_b16 v[224:225], v178 offset:0x1c00
	s_waitcnt lgkmcnt(4)
	v_mfma_f32_32x32x16_bf16 v[32:47], v[166:169], v[226:229], v[32:47]
	v_max3_f32 v253, v253, v68, v69
	v_max3_f32 v253, v253, v70, v71
	v_mfma_f32_32x32x16_bf16 v[32:47], v[170:173], v[230:233], v[32:47]
	v_max3_f32 v253, v253, v72, v73
	v_max3_f32 v253, v253, v74, v75
	ds_read_b64_tr_b16 v[226:227], v178 offset:0x2400
	ds_read_b64_tr_b16 v[228:229], v178 offset:0x2c00
	ds_read_b64_tr_b16 v[230:231], v178 offset:0x3400
	ds_read_b64_tr_b16 v[232:233], v178 offset:0x3c00
	s_waitcnt lgkmcnt(4)
	v_mfma_f32_32x32x16_bf16 v[16:31], v[158:161], v[174:177], v[16:31]
	v_max3_f32 v253, v253, v76, v77
	v_max3_f32 v253, v253, v78, v79
	v_mfma_f32_32x32x16_bf16 v[16:31], v[162:165], v[222:225], v[16:31]
	v_mov_b32_e32 v254, v253
	s_nop 1
	ds_read_b64_tr_b16 v[174:175], v178 offset:0x600
	ds_read_b64_tr_b16 v[176:177], v178 offset:0xe00
	ds_read_b64_tr_b16 v[222:223], v178 offset:0x1600
	ds_read_b64_tr_b16 v[224:225], v178 offset:0x1e00
	s_waitcnt lgkmcnt(4)
	v_mfma_f32_32x32x16_bf16 v[16:31], v[166:169], v[226:229], v[16:31]
	v_permlane32_swap_b32_e32 v253, v254
	v_max_f32_e32 v254, v254, v254
	v_mfma_f32_32x32x16_bf16 v[16:31], v[170:173], v[230:233], v[16:31]
	v_max_f32_e32 v253, v253, v253
	v_max_f32_e32 v253, v253, v254
	ds_read_b64_tr_b16 v[226:227], v178 offset:0x2600
	ds_read_b64_tr_b16 v[228:229], v178 offset:0x2e00
	ds_read_b64_tr_b16 v[230:231], v178 offset:0x3600
	ds_read_b64_tr_b16 v[232:233], v178 offset:0x3e00
	s_waitcnt lgkmcnt(4)
	v_mfma_f32_32x32x16_bf16 v[0:15], v[158:161], v[174:177], v[0:15]
	v_sub_f32_e32 v254, v253, v154
	v_cmp_ge_f32_e32 vcc, s33, v254
	v_mfma_f32_32x32x16_bf16 v[0:15], v[162:165], v[222:225], v[0:15]
	v_max_f32_e32 v254, v154, v154
	v_max_f32_e32 v254, v254, v253
	s_waitcnt lgkmcnt(0)
	v_mfma_f32_32x32x16_bf16 v[0:15], v[166:169], v[226:229], v[0:15]
	v_sub_f32_e32 v253, v154, v254
	v_exp_f32_e32 v253, v253
	v_mfma_f32_32x32x16_bf16 v[0:15], v[170:173], v[230:233], v[0:15]
	v_mov_b32_e32 v158, v253
	v_mov_b32_e32 v159, v254
	s_branch .Lmaxtail_1

; __device__ __forceinline__ void partialSM(f32x16& p0, f32x16& p1, float& m_reg, float& mn, float& alpha) {
;     ...
;     for (int r = 0; r < 16; ++r) p0[r] = p0[r] - mn;
; #pragma unroll
;     for (int r = 0; r < 16; ++r) p1[r] = p1[r] - mn;
; #pragma unroll
;     for (int r = 0; r < 16; ++r) p0[r] = __builtin_amdgcn_exp2f(p0[r]);
.LBB0_543:
	v_cndmask_b32_e64 v154, v159, v154, s[2:3]
	v_pk_add_f32 v[80:81], v[80:81], v[154:155] op_sel_hi:[1,0] neg_lo:[0,1] neg_hi:[0,1]
	v_pk_add_f32 v[82:83], v[82:83], v[154:155] op_sel_hi:[1,0] neg_lo:[0,1] neg_hi:[0,1]
	v_pk_add_f32 v[84:85], v[84:85], v[154:155] op_sel_hi:[1,0] neg_lo:[0,1] neg_hi:[0,1]
	v_pk_add_f32 v[86:87], v[86:87], v[154:155] op_sel_hi:[1,0] neg_lo:[0,1] neg_hi:[0,1]
	v_pk_add_f32 v[88:89], v[88:89], v[154:155] op_sel_hi:[1,0] neg_lo:[0,1] neg_hi:[0,1]
	v_pk_add_f32 v[90:91], v[90:91], v[154:155] op_sel_hi:[1,0] neg_lo:[0,1] neg_hi:[0,1]
	v_pk_add_f32 v[92:93], v[92:93], v[154:155] op_sel_hi:[1,0] neg_lo:[0,1] neg_hi:[0,1]
	v_pk_add_f32 v[94:95], v[94:95], v[154:155] op_sel_hi:[1,0] neg_lo:[0,1] neg_hi:[0,1]
	v_exp_f32_e32 v221, v80
	v_exp_f32_e32 v236, v81
	v_exp_f32_e32 v233, v82
	v_exp_f32_e32 v235, v83
	v_exp_f32_e32 v231, v84
	v_exp_f32_e32 v234, v85
	v_exp_f32_e32 v230, v86
	v_exp_f32_e32 v232, v87
	v_exp_f32_e32 v227, v88
	v_exp_f32_e32 v229, v89
	v_exp_f32_e32 v225, v90
	v_exp_f32_e32 v228, v91
	v_exp_f32_e32 v223, v92
	v_exp_f32_e32 v226, v93
	v_exp_f32_e32 v222, v94
	v_exp_f32_e32 v224, v95
	s_mov_b64 s[2:3], -1
	s_and_b64 vcc, exec, s[86:87]
	s_cbranch_vccz .LBB0_549
	s_and_b64 vcc, exec, s[96:97]
	s_cbranch_vccz .LBB0_546
	s_waitcnt vmcnt(0) lgkmcnt(0)
	s_barrier
	s_mov_b64 s[2:3], 0

; #define LAS __attribute__((address_space(3)))
; __device__ __forceinline__ void partialSM(f32x16& p0, f32x16& p1, float& m_reg, float& mn, float& alpha) {
;     ...
;     for (int r = 0; r < 16; ++r) p0[r] = p0[r] - mn;
; #pragma unroll
;     for (int r = 0; r < 16; ++r) p1[r] = p1[r] - mn;
; #pragma unroll
;     for (int r = 0; r < 16; ++r) p0[r] = __builtin_amdgcn_exp2f(p0[r]);
; }
; __device__ __forceinline__ void finishSM(f32x16& p0, f32x16& p1, float alpha, float& l_reg, bf16x8& pa0, bf16x8& pa1, bf16x8& pa2, bf16x8& pa3) {
; #pragma unroll
;     for (int r = 0; r < 16; ++r) p1[r] = __builtin_amdgcn_exp2f(p1[r]);
;     float ps = 0;
; #pragma unroll
;     for (int r = 0; r < 16; ++r) ps += p0[r];
; #pragma unroll
;     for (int r = 0; r < 16; ++r) ps += p1[r];
;     { auto rr = __builtin_amdgcn_permlane32_swap(__float_as_uint(ps), __float_as_uint(ps), false, false);
;       ps = __uint_as_float(rr[0]) + __uint_as_float(rr[1]); }
;     l_reg = l_reg * alpha + ps;
;     ...
;     PK4(p0, 0, pa0); PK4(p0, 8, pa1); PK4(p1, 0, pa2); PK4(p1, 8, pa3);
; __device__ __forceinline__ void qkt(f32x16& p0, f32x16& p1, const char* Kslot, int r32, int hi, const bf16x8* qr, const LAS f32x4* cp) {
; #pragma unroll
;     for (int g = 0; g < 4; ++g) { const f32x4 c0 = cp[2 * g], c1 = cp[8 + 2 * g];
; #pragma unroll
;         for (int j = 0; j < 4; ++j) { p0[4 * g + j] = c0[j]; p1[4 * g + j] = c1[j]; } }
;     const char* kb[4];
; #pragma unroll
;     for (int dd = 0; dd < 4; ++dd) kb[dd] = Kslot + KSWZ(r32, (dd * 16 + hi * 8) * 2);
; #pragma unroll
;     for (int d0 = 0; d0 < 8; ++d0) { const char* a = kb[d0 & 3] + (d0 >> 2) * 128;
;         bf16x8 b0 = *reinterpret_cast<const bf16x8*>(a);
;         bf16x8 b1 = *reinterpret_cast<const bf16x8*>(a + 32 * 256);
;         p0 = __builtin_amdgcn_mfma_f32_32x32x16_bf16(b0, qr[d0], p0, 0, 0, 0);
;         p1 = __builtin_amdgcn_mfma_f32_32x32x16_bf16(b1, qr[d0], p1, 0, 0, 0); }
.LBB0_572:
	v_cndmask_b32_e64 v144, v154, v144, s[2:3]
	v_pk_add_f32 v[80:81], v[80:81], v[144:145] op_sel_hi:[1,0] neg_lo:[0,1] neg_hi:[0,1]
	v_pk_add_f32 v[82:83], v[82:83], v[144:145] op_sel_hi:[1,0] neg_lo:[0,1] neg_hi:[0,1]
	v_pk_add_f32 v[84:85], v[84:85], v[144:145] op_sel_hi:[1,0] neg_lo:[0,1] neg_hi:[0,1]
	v_pk_add_f32 v[86:87], v[86:87], v[144:145] op_sel_hi:[1,0] neg_lo:[0,1] neg_hi:[0,1]
	v_pk_add_f32 v[88:89], v[88:89], v[144:145] op_sel_hi:[1,0] neg_lo:[0,1] neg_hi:[0,1]
	v_pk_add_f32 v[90:91], v[90:91], v[144:145] op_sel_hi:[1,0] neg_lo:[0,1] neg_hi:[0,1]
	v_pk_add_f32 v[92:93], v[92:93], v[144:145] op_sel_hi:[1,0] neg_lo:[0,1] neg_hi:[0,1]
	v_pk_add_f32 v[94:95], v[94:95], v[144:145] op_sel_hi:[1,0] neg_lo:[0,1] neg_hi:[0,1]
	v_pk_add_f32 v[154:155], v[64:65], v[144:145] op_sel_hi:[1,0] neg_lo:[0,1] neg_hi:[0,1]
	v_pk_add_f32 v[156:157], v[66:67], v[144:145] op_sel_hi:[1,0] neg_lo:[0,1] neg_hi:[0,1]
	v_pk_add_f32 v[158:159], v[68:69], v[144:145] op_sel_hi:[1,0] neg_lo:[0,1] neg_hi:[0,1]
	v_pk_add_f32 v[160:161], v[70:71], v[144:145] op_sel_hi:[1,0] neg_lo:[0,1] neg_hi:[0,1]
	v_pk_add_f32 v[162:163], v[72:73], v[144:145] op_sel_hi:[1,0] neg_lo:[0,1] neg_hi:[0,1]
	v_pk_add_f32 v[164:165], v[74:75], v[144:145] op_sel_hi:[1,0] neg_lo:[0,1] neg_hi:[0,1]
	v_sub_f32_e32 v166, v76, v144
	v_exp_f32_e32 v167, v80
	v_exp_f32_e32 v168, v81
	v_exp_f32_e32 v169, v82
	v_exp_f32_e32 v178, v83
	v_exp_f32_e32 v179, v84
	v_exp_f32_e32 v198, v85
	v_exp_f32_e32 v199, v86
	v_exp_f32_e32 v200, v87
	v_exp_f32_e32 v201, v88
	v_exp_f32_e32 v202, v89
	v_exp_f32_e32 v203, v90
	v_exp_f32_e32 v204, v91
	v_exp_f32_e32 v205, v92
	v_exp_f32_e32 v206, v93
	v_exp_f32_e32 v207, v94
	v_exp_f32_e32 v208, v95
	v_sub_f32_e32 v209, v77, v144
	v_pk_add_f32 v[210:211], v[78:79], v[144:145] op_sel_hi:[1,0] neg_lo:[0,1] neg_hi:[0,1]
	s_add_i32 s2, s90, 0
	v_add_u32_e32 v212, s2, v193
	ds_read_b128 v[80:83], v197 offset:256
	ds_read_b128 v[84:87], v197 offset:288
	ds_read_b128 v[64:67], v197 offset:384
	ds_read_b128 v[68:71], v197 offset:416
	ds_read_b128 v[88:91], v197 offset:320
	ds_read_b128 v[72:75], v197 offset:448
	ds_read_b128 v[92:95], v197 offset:352
	ds_read_b128 v[76:79], v197 offset:480
	ds_read_b128 v[146:149], v212 offset:49152
	ds_read_b128 v[150:153], v212 offset:57344
	v_add_u32_e32 v213, s2, v194
	v_add_u32_e32 v214, s2, v195
	s_waitcnt lgkmcnt(0)
	v_mfma_f32_32x32x16_bf16 v[80:95], v[146:149], v[96:99], v[80:95]
	v_add_u32_e32 v215, s2, v196
	v_exp_f32_e32 v157, v157
	v_exp_f32_e32 v158, v158
	v_exp_f32_e32 v159, v159
	v_exp_f32_e32 v160, v160
	v_exp_f32_e32 v161, v161
	v_exp_f32_e32 v162, v162
	v_mfma_f32_32x32x16_bf16 v[64:79], v[150:153], v[96:99], v[64:79]
	ds_read_b128 v[146:149], v213 offset:49152
	ds_read_b128 v[150:153], v213 offset:57344
	v_exp_f32_e32 v163, v163
	v_exp_f32_e32 v164, v164
	v_exp_f32_e32 v165, v165
	v_exp_f32_e32 v166, v166
	v_exp_f32_e32 v209, v209
	v_exp_f32_e32 v210, v210
	s_waitcnt lgkmcnt(0)
	v_mfma_f32_32x32x16_bf16 v[80:95], v[146:149], v[100:103], v[80:95]
	v_exp_f32_e32 v211, v211
	v_mfma_f32_32x32x16_bf16 v[64:79], v[150:153], v[100:103], v[64:79]
	ds_read_b128 v[146:149], v214 offset:49152
	ds_read_b128 v[150:153], v214 offset:57344
	s_waitcnt lgkmcnt(0)
	v_mfma_f32_32x32x16_bf16 v[80:95], v[146:149], v[104:107], v[80:95]
	v_mfma_f32_32x32x16_bf16 v[64:79], v[150:153], v[104:107], v[64:79]
	ds_read_b128 v[146:149], v215 offset:49152
	ds_read_b128 v[150:153], v215 offset:57344
	s_waitcnt lgkmcnt(0)
	v_mfma_f32_32x32x16_bf16 v[80:95], v[146:149], v[108:111], v[80:95]
	v_mfma_f32_32x32x16_bf16 v[64:79], v[150:153], v[108:111], v[64:79]
	v_xor_b32_e32 v249, 0x80, v212
	v_xor_b32_e32 v250, 0x80, v213
	v_xor_b32_e32 v251, 0x80, v214
	v_xor_b32_e32 v252, 0x80, v215
	ds_read_b128 v[146:149], v249 offset:49152
	ds_read_b128 v[150:153], v249 offset:57344
	v_exp_f32_e32 v212, v154
	s_waitcnt lgkmcnt(0)
	v_mfma_f32_32x32x16_bf16 v[80:95], v[146:149], v[112:115], v[80:95]
	v_mfma_f32_32x32x16_bf16 v[64:79], v[150:153], v[112:115], v[64:79]
	ds_read_b128 v[146:149], v250 offset:49152
	ds_read_b128 v[150:153], v250 offset:57344
	v_exp_f32_e32 v213, v155
	s_waitcnt lgkmcnt(0)
	v_mfma_f32_32x32x16_bf16 v[80:95], v[146:149], v[116:119], v[80:95]
	v_mfma_f32_32x32x16_bf16 v[64:79], v[150:153], v[116:119], v[64:79]
	ds_read_b128 v[146:149], v251 offset:49152
	ds_read_b128 v[150:153], v251 offset:57344
	v_exp_f32_e32 v214, v156
	s_waitcnt lgkmcnt(0)
	v_mfma_f32_32x32x16_bf16 v[80:95], v[146:149], v[120:123], v[80:95]
	v_mfma_f32_32x32x16_bf16 v[64:79], v[150:153], v[120:123], v[64:79]
	ds_read_b128 v[146:149], v252 offset:49152
	ds_read_b128 v[150:153], v252 offset:57344
	s_waitcnt lgkmcnt(0)
	v_mfma_f32_32x32x16_bf16 v[80:95], v[146:149], v[124:127], v[80:95]
	v_add_f32_e32 v146, 0, v167
	v_add_f32_e32 v146, v168, v146
	v_add_f32_e32 v146, v169, v146
	v_add_f32_e32 v146, v178, v146
	v_add_f32_e32 v146, v179, v146
	v_add_f32_e32 v146, v198, v146
	v_add_f32_e32 v146, v199, v146
	v_add_f32_e32 v146, v200, v146
	v_add_f32_e32 v146, v201, v146
	v_add_f32_e32 v146, v202, v146
	v_add_f32_e32 v146, v203, v146
	v_add_f32_e32 v146, v204, v146
	v_add_f32_e32 v146, v205, v146
	v_add_f32_e32 v146, v206, v146
	v_add_f32_e32 v146, v207, v146
	v_add_f32_e32 v146, v208, v146
	v_add_f32_e32 v146, v212, v146
	v_add_f32_e32 v146, v213, v146
	v_add_f32_e32 v146, v214, v146
	v_add_f32_e32 v146, v157, v146
	v_add_f32_e32 v146, v158, v146
	v_add_f32_e32 v146, v159, v146
	v_add_f32_e32 v146, v160, v146
	v_add_f32_e32 v146, v161, v146
	v_add_f32_e32 v146, v162, v146
	v_add_f32_e32 v146, v163, v146
	v_mfma_f32_32x32x16_bf16 v[64:79], v[150:153], v[124:127], v[64:79]
	v_add_f32_e32 v146, v164, v146
	v_add_f32_e32 v146, v165, v146
	v_add_f32_e32 v146, v166, v146
	v_add_f32_e32 v146, v209, v146
	v_add_f32_e32 v146, v210, v146
	v_add_f32_e32 v146, v211, v146
	v_mov_b32_e32 v147, v146
	s_nop 1
	v_permlane32_swap_b32_e32 v146, v147
	v_cvt_pk_bf16_f32 v148, v167, v168
	v_cvt_pk_bf16_f32 v149, v169, v178
	v_cvt_pk_bf16_f32 v150, v179, v198
	v_cvt_pk_bf16_f32 v151, v199, v200
	v_cvt_pk_bf16_f32 v152, v201, v202
	v_cvt_pk_bf16_f32 v153, v203, v204
	v_cvt_pk_bf16_f32 v154, v205, v206
	v_cvt_pk_bf16_f32 v155, v207, v208
	v_cvt_pk_bf16_f32 v156, v212, v213
	v_cvt_pk_bf16_f32 v157, v214, v157
	v_cvt_pk_bf16_f32 v158, v158, v159
	v_cvt_pk_bf16_f32 v159, v160, v161
	v_cvt_pk_bf16_f32 v160, v162, v163
	v_cvt_pk_bf16_f32 v161, v164, v165
	v_cvt_pk_bf16_f32 v162, v166, v209
	v_cvt_pk_bf16_f32 v163, v210, v211
	s_nop 0
	v_permlane32_swap_b32_e32 v148, v150
	v_permlane32_swap_b32_e32 v149, v151
	v_permlane32_swap_b32_e32 v152, v154
	v_permlane32_swap_b32_e32 v153, v155
	v_permlane32_swap_b32_e32 v156, v158
	v_permlane32_swap_b32_e32 v157, v159
	v_permlane32_swap_b32_e32 v160, v162
	v_permlane32_swap_b32_e32 v161, v163
	v_add_u32_e32 v168, s73, v192
	s_cmp_le_i32 s91, s88
	s_cbranch_scc0 .Lband_3
; #define SBAR() __builtin_amdgcn_sched_barrier(0)
; #define PV_RD(d0, kh, X) do { constexpr int b_ = v_rd_off(d0, 2 * (kh), 0); TRRD(X##l0, b_); TRRD(X##h0, b_ + 2048); TRRD(X##l1, b_ + 4096); TRRD(X##h1, b_ + 6144); } while (0)
; #define PV_MM(d0, X, PA, PB) do { \
;         o[d0] = __builtin_amdgcn_mfma_f32_32x32x16_bf16(PA, (bf16x8){X##l0[0], X##l0[1], X##l0[2], X##l0[3], X##h0[0], X##h0[1], X##h0[2], X##h0[3]}, o[d0], 0, 0, 0);   \
;         o[d0] = __builtin_amdgcn_mfma_f32_32x32x16_bf16(PB, (bf16x8){X##l1[0], X##l1[1], X##l1[2], X##l1[3], X##h1[0], X##h1[1], X##h1[2], X##h1[3]}, o[d0], 0, 0, 0); } while (0)
; #define PV_W4() do { asm volatile("s_waitcnt lgkmcnt(4)" ::: "memory"); SBAR(); } while (0)
; #define PV_W0() do { asm volatile("s_waitcnt lgkmcnt(0)" ::: "memory"); SBAR(); } while (0)
; __device__ __forceinline__ void partialSM(f32x16& p0, f32x16& p1, float& m_reg, float& mn, float& alpha) {
;     float pmax = p0[0];
; #pragma unroll
;     for (int r = 1; r < 16; ++r) pmax = fmaxf(pmax, p0[r]);
; #pragma unroll
;     for (int r = 0; r < 16; ++r) pmax = fmaxf(pmax, p1[r]);
;     { auto rr = __builtin_amdgcn_permlane32_swap(__float_as_uint(pmax), __float_as_uint(pmax), false, false);
;       pmax = fmaxf(__uint_as_float(rr[0]), __uint_as_float(rr[1])); }
;     if (__builtin_expect(__all((pmax - m_reg) <= THR2), 1)) { mn = m_reg; alpha = 1.f; }
;     else { mn = fmaxf(m_reg, pmax); alpha = __builtin_amdgcn_exp2f(m_reg - mn); m_reg = mn; }
; __device__ __forceinline__ void pv_tile(f32x16* o, int vb0, bf16x8 pa0, bf16x8 pa1, bf16x8 pa2, bf16x8 pa3) {
;     ...
;     s16x4 al0, al1, ah0, ah1, bl0, bl1, bh0, bh1;
;     PV_RD(0, 0, a);
;     PV_RD(0, 1, b); PV_W4(); PV_MM(0, a, pa0, pa1); SBAR();
;     PV_RD(1, 0, a); PV_W4(); PV_MM(0, b, pa2, pa3); SBAR();
;     PV_RD(1, 1, b); PV_W4(); PV_MM(1, a, pa0, pa1); SBAR();
;     PV_RD(2, 0, a); PV_W4(); PV_MM(1, b, pa2, pa3); SBAR();
;     PV_RD(2, 1, b); PV_W4(); PV_MM(2, a, pa0, pa1); SBAR();
;     PV_RD(3, 0, a); PV_W4(); PV_MM(2, b, pa2, pa3); SBAR();
;     PV_RD(3, 1, b); PV_W4(); PV_MM(3, a, pa0, pa1); SBAR();
;     PV_W0(); PV_MM(3, b, pa2, pa3);
	ds_read_b64_tr_b16 v[164:165], v168 offset:0
	ds_read_b64_tr_b16 v[166:167], v168 offset:0x800
	ds_read_b64_tr_b16 v[198:199], v168 offset:0x1000
	ds_read_b64_tr_b16 v[200:201], v168 offset:0x1800
	ds_read_b64_tr_b16 v[202:203], v168 offset:0x2000
	ds_read_b64_tr_b16 v[204:205], v168 offset:0x2800
	ds_read_b64_tr_b16 v[206:207], v168 offset:0x3000
	ds_read_b64_tr_b16 v[208:209], v168 offset:0x3800
	s_waitcnt lgkmcnt(4)
	s_nop 0
	v_mfma_f32_32x32x16_bf16 v[48:63], v[148:151], v[164:167], v[48:63]
	v_max_f32_e32 v253, v81, v81
	v_max_f32_e32 v254, v80, v80
	v_mfma_f32_32x32x16_bf16 v[48:63], v[152:155], v[198:201], v[48:63]
	v_max_f32_e32 v253, v254, v253
	v_max3_f32 v253, v253, v82, v83
	ds_read_b64_tr_b16 v[164:165], v168 offset:0x200
	ds_read_b64_tr_b16 v[166:167], v168 offset:0xa00
	ds_read_b64_tr_b16 v[198:199], v168 offset:0x1200
	ds_read_b64_tr_b16 v[200:201], v168 offset:0x1a00
	s_waitcnt lgkmcnt(4)
	v_mfma_f32_32x32x16_bf16 v[48:63], v[156:159], v[202:205], v[48:63]
	v_max3_f32 v253, v253, v84, v85
	v_max3_f32 v253, v253, v86, v87
	v_mfma_f32_32x32x16_bf16 v[48:63], v[160:163], v[206:209], v[48:63]
	v_max3_f32 v253, v253, v88, v89
	v_max3_f32 v253, v253, v90, v91
	ds_read_b64_tr_b16 v[202:203], v168 offset:0x2200
	ds_read_b64_tr_b16 v[204:205], v168 offset:0x2a00
	ds_read_b64_tr_b16 v[206:207], v168 offset:0x3200
	ds_read_b64_tr_b16 v[208:209], v168 offset:0x3a00
	s_waitcnt lgkmcnt(4)
	v_mfma_f32_32x32x16_bf16 v[32:47], v[148:151], v[164:167], v[32:47]
	v_max3_f32 v253, v253, v92, v93
	v_max3_f32 v253, v253, v94, v95
	v_mfma_f32_32x32x16_bf16 v[32:47], v[152:155], v[198:201], v[32:47]
	v_max3_f32 v253, v253, v64, v65
	v_max3_f32 v253, v253, v66, v67
	ds_read_b64_tr_b16 v[164:165], v168 offset:0x400
	ds_read_b64_tr_b16 v[166:167], v168 offset:0xc00
	ds_read_b64_tr_b16 v[198:199], v168 offset:0x1400
	ds_read_b64_tr_b16 v[200:201], v168 offset:0x1c00
	s_waitcnt lgkmcnt(4)
	v_mfma_f32_32x32x16_bf16 v[32:47], v[156:159], v[202:205], v[32:47]
	v_max3_f32 v253, v253, v68, v69
	v_max3_f32 v253, v253, v70, v71
	v_mfma_f32_32x32x16_bf16 v[32:47], v[160:163], v[206:209], v[32:47]
	v_max3_f32 v253, v253, v72, v73
	v_max3_f32 v253, v253, v74, v75
	ds_read_b64_tr_b16 v[202:203], v168 offset:0x2400
	ds_read_b64_tr_b16 v[204:205], v168 offset:0x2c00
	ds_read_b64_tr_b16 v[206:207], v168 offset:0x3400
	ds_read_b64_tr_b16 v[208:209], v168 offset:0x3c00
	s_waitcnt lgkmcnt(4)
	v_mfma_f32_32x32x16_bf16 v[16:31], v[148:151], v[164:167], v[16:31]
	v_max3_f32 v253, v253, v76, v77
	v_max3_f32 v253, v253, v78, v79
	v_mfma_f32_32x32x16_bf16 v[16:31], v[152:155], v[198:201], v[16:31]
	v_mov_b32_e32 v254, v253
	s_nop 1
	ds_read_b64_tr_b16 v[164:165], v168 offset:0x600
	ds_read_b64_tr_b16 v[166:167], v168 offset:0xe00
	ds_read_b64_tr_b16 v[198:199], v168 offset:0x1600
	ds_read_b64_tr_b16 v[200:201], v168 offset:0x1e00
	s_waitcnt lgkmcnt(4)
	v_mfma_f32_32x32x16_bf16 v[16:31], v[156:159], v[202:205], v[16:31]
	v_permlane32_swap_b32_e32 v253, v254
	v_max_f32_e32 v254, v254, v254
	v_mfma_f32_32x32x16_bf16 v[16:31], v[160:163], v[206:209], v[16:31]
	v_max_f32_e32 v253, v253, v253
	v_max_f32_e32 v253, v253, v254
	ds_read_b64_tr_b16 v[202:203], v168 offset:0x2600
	ds_read_b64_tr_b16 v[204:205], v168 offset:0x2e00
	ds_read_b64_tr_b16 v[206:207], v168 offset:0x3600
	ds_read_b64_tr_b16 v[208:209], v168 offset:0x3e00
	s_waitcnt lgkmcnt(4)
	v_mfma_f32_32x32x16_bf16 v[0:15], v[148:151], v[164:167], v[0:15]
	v_sub_f32_e32 v254, v253, v144
	v_cmp_ge_f32_e32 vcc, s33, v254
	v_mfma_f32_32x32x16_bf16 v[0:15], v[152:155], v[198:201], v[0:15]
	v_max_f32_e32 v254, v144, v144
	v_max_f32_e32 v254, v254, v253
	s_waitcnt lgkmcnt(0)
	v_mfma_f32_32x32x16_bf16 v[0:15], v[156:159], v[202:205], v[0:15]
	v_sub_f32_e32 v253, v144, v254
	v_exp_f32_e32 v253, v253
	v_mfma_f32_32x32x16_bf16 v[0:15], v[160:163], v[206:209], v[0:15]
	v_mov_b32_e32 v148, v253
	v_mov_b32_e32 v149, v254
	s_branch .Lmaxtail_3

; __device__ __forceinline__ void partialSM(f32x16& p0, f32x16& p1, float& m_reg, float& mn, float& alpha) {
;     ...
; #pragma unroll
;     for (int r = 0; r < 16; ++r) p0[r] = p0[r] - mn;
; #pragma unroll
;     for (int r = 0; r < 16; ++r) p1[r] = p1[r] - mn;
; #pragma unroll
;     for (int r = 0; r < 16; ++r) p0[r] = __builtin_amdgcn_exp2f(p0[r]);
.LBB0_578:
	v_cndmask_b32_e64 v144, v149, v144, s[2:3]
	v_pk_add_f32 v[80:81], v[80:81], v[144:145] op_sel_hi:[1,0] neg_lo:[0,1] neg_hi:[0,1]
	v_pk_add_f32 v[82:83], v[82:83], v[144:145] op_sel_hi:[1,0] neg_lo:[0,1] neg_hi:[0,1]
	v_pk_add_f32 v[84:85], v[84:85], v[144:145] op_sel_hi:[1,0] neg_lo:[0,1] neg_hi:[0,1]
	v_pk_add_f32 v[86:87], v[86:87], v[144:145] op_sel_hi:[1,0] neg_lo:[0,1] neg_hi:[0,1]
	v_pk_add_f32 v[88:89], v[88:89], v[144:145] op_sel_hi:[1,0] neg_lo:[0,1] neg_hi:[0,1]
	v_pk_add_f32 v[90:91], v[90:91], v[144:145] op_sel_hi:[1,0] neg_lo:[0,1] neg_hi:[0,1]
	v_pk_add_f32 v[92:93], v[92:93], v[144:145] op_sel_hi:[1,0] neg_lo:[0,1] neg_hi:[0,1]
	v_pk_add_f32 v[94:95], v[94:95], v[144:145] op_sel_hi:[1,0] neg_lo:[0,1] neg_hi:[0,1]
	v_exp_f32_e32 v178, v80
	v_exp_f32_e32 v211, v81
	v_exp_f32_e32 v208, v82
	v_exp_f32_e32 v210, v83
	v_exp_f32_e32 v206, v84
	v_exp_f32_e32 v209, v85
	v_exp_f32_e32 v205, v86
	v_exp_f32_e32 v207, v87
	v_exp_f32_e32 v202, v88
	v_exp_f32_e32 v204, v89
	v_exp_f32_e32 v200, v90
	v_exp_f32_e32 v203, v91
	v_exp_f32_e32 v198, v92
	v_exp_f32_e32 v201, v93
	v_exp_f32_e32 v179, v94
	v_exp_f32_e32 v199, v95
	s_mov_b64 s[2:3], -1
	s_and_b64 vcc, exec, s[76:77]
	s_cbranch_vccz .LBB0_584
	s_and_b64 vcc, exec, s[66:67]
	s_cbranch_vccz .LBB0_581
	s_waitcnt vmcnt(0) lgkmcnt(0)
	s_barrier
	s_mov_b64 s[2:3], 0
